# baseline (speedup 1.0000x reference)
.LBB0_32:
	s_or_b64 exec, exec, s[36:37]
	s_waitcnt vmcnt(63)
	s_mov_b32 s23, -2
	s_mov_b64 s[40:41], s[18:19]
	s_mov_b64 s[42:43], s[16:17]
	s_barrier
	s_barrier
	.p2align 6

.LBB0_76:
	s_or_b64 exec, exec, s[36:37]
	s_waitcnt vmcnt(63)
	s_mov_b32 s36, -2
	s_mov_b64 s[38:39], s[22:23]
	s_mov_b64 s[40:41], s[14:15]
	s_mov_b64 s[76:77], 0xb0080
	s_mov_b64 s[78:79], 0x108080
	s_barrier
	s_barrier
	.p2align 6

.LBB0_98:
	s_or_b64 exec, exec, s[22:23]
	s_waitcnt vmcnt(32)
	s_mov_b32 s18, -2
	s_mov_b64 s[22:23], s[70:71]
	s_mov_b64 s[38:39], s[68:69]
	s_barrier
	s_barrier
	.p2align 6

.LBB0_134:
	s_or_b64 exec, exec, s[22:23]
	s_add_u32 s22, s38, s86
	s_addc_u32 s23, s39, 0
	s_add_u32 s42, s14, s86
	s_addc_u32 s43, s15, 0
	s_add_u32 s46, s14, s34
	s_addc_u32 s47, s15, 0
	s_add_u32 s68, s38, s34
	s_addc_u32 s69, s39, 0
	s_add_u32 s70, s14, s18
	s_waitcnt vmcnt(63)
	s_addc_u32 s71, s15, 0
	s_add_u32 s76, s38, s18
	s_addc_u32 s77, s39, 0
	s_mov_b32 s81, 0
	s_mov_b64 s[78:79], s[38:39]
	s_mov_b64 vcc, s[14:15]
	s_barrier
	s_barrier
	.p2align 6

.LBB0_193:
	s_nop 7
	v_max_f32_e32 v34, v17, v17
	v_max_f32_e32 v35, v16, v16
	v_max_f32_e32 v34, v35, v34
	v_max3_f32 v34, v34, v18, v19
	v_max3_f32 v34, v34, v20, v21
	v_max3_f32 v34, v34, v22, v23
	v_max3_f32 v34, v34, v24, v25
	v_max3_f32 v34, v34, v26, v27
	v_max3_f32 v34, v34, v28, v29
	v_max3_f32 v34, v34, v30, v31
	v_max3_f32 v34, v34, v0, v1
	v_max3_f32 v34, v34, v2, v3
	v_max3_f32 v34, v34, v4, v5
	v_max3_f32 v34, v34, v6, v7
	v_max3_f32 v34, v34, v8, v9
	v_max3_f32 v34, v34, v10, v11
	v_max3_f32 v34, v34, v12, v13
	v_max3_f32 v34, v34, v14, v15
	v_mov_b32_e32 v35, v34
	s_nop 1
	v_permlane32_swap_b32_e32 v34, v35
	v_max_f32_e32 v35, v35, v35
	v_max_f32_e32 v34, v34, v34
	v_max_f32_e32 v34, v34, v35
	v_add_f32_e32 v35, 0x7149f2ca, v34
	v_mul_f32_e32 v35, 0x3e000000, v35
	s_mov_b32 s8, 0x41800000
	v_cmp_ge_f32_e32 vcc, s8, v35
	s_cmp_eq_u64 vcc, exec
	s_cselect_b64 vcc, -1, 0
	v_cmp_lt_i32_e64 s[8:9], 3, v32
	s_and_saveexec_b64 s[10:11], s[8:9]
	s_setprio 1
	s_or_b64 exec, exec, s[10:11]
	v_max_f32_e32 v34, 0xf149f2ca, v34
	v_mov_b32_e32 v32, 0xf149f2ca
	v_cndmask_b32_e32 v163, v34, v32, vcc
	v_mul_f32_e32 v32, 0xbe38aa3b, v163
	v_fmamk_f32 v16, v16, 0x3e38aa3b, v32
	v_exp_f32_e32 v188, v16
	v_sub_f32_e32 v16, 0xf149f2ca, v34
	v_mul_f32_e32 v16, 0x3e38aa3b, v16
	v_fmamk_f32 v17, v17, 0x3e38aa3b, v32
	v_fmamk_f32 v18, v18, 0x3e38aa3b, v32
	v_fmamk_f32 v19, v19, 0x3e38aa3b, v32
	v_fmamk_f32 v20, v20, 0x3e38aa3b, v32
	v_fmamk_f32 v21, v21, 0x3e38aa3b, v32
	v_fmamk_f32 v22, v22, 0x3e38aa3b, v32
	v_fmamk_f32 v23, v23, 0x3e38aa3b, v32
	v_fmamk_f32 v24, v24, 0x3e38aa3b, v32
	v_fmamk_f32 v25, v25, 0x3e38aa3b, v32
	v_fmamk_f32 v26, v26, 0x3e38aa3b, v32
	v_fmamk_f32 v27, v27, 0x3e38aa3b, v32
	v_fmamk_f32 v28, v28, 0x3e38aa3b, v32
	v_fmamk_f32 v29, v29, 0x3e38aa3b, v32
	v_fmamk_f32 v30, v30, 0x3e38aa3b, v32
	v_fmamk_f32 v31, v31, 0x3e38aa3b, v32
	v_exp_f32_e32 v16, v16
	v_exp_f32_e32 v190, v17
	v_exp_f32_e32 v186, v18
	v_exp_f32_e32 v189, v19
	v_exp_f32_e32 v184, v20
	v_exp_f32_e32 v187, v21
	v_exp_f32_e32 v183, v22
	v_exp_f32_e32 v185, v23
	v_exp_f32_e32 v171, v24
	v_exp_f32_e32 v180, v25
	v_exp_f32_e32 v170, v26
	v_exp_f32_e32 v172, v27
	v_exp_f32_e32 v169, v28
	v_exp_f32_e32 v182, v29
	v_exp_f32_e32 v173, v30
	v_exp_f32_e32 v181, v31
	v_pk_fma_f32 v[138:139], v[2:3], s[82:83], v[32:33] op_sel_hi:[1,0,0]
	v_pk_fma_f32 v[140:141], v[0:1], s[82:83], v[32:33] op_sel_hi:[1,0,0]
	v_and_b32_e32 v0, 0x3fffffc0, v143
	v_lshlrev_b32_e32 v2, 6, v143
	v_lshlrev_b32_e32 v0, 2, v0
	v_and_b32_e32 v1, 0x78, v33
	v_and_b32_e32 v2, 0x400, v2
	v_lshlrev_b32_e32 v3, 8, v146
	s_add_i32 s8, s3, 2
	v_cndmask_b32_e64 v149, v16, 1.0, vcc
	v_pk_fma_f32 v[86:87], v[14:15], s[82:83], v[32:33] op_sel_hi:[1,0,0]
	v_pk_fma_f32 v[88:89], v[12:13], s[82:83], v[32:33] op_sel_hi:[1,0,0]
	v_pk_fma_f32 v[90:91], v[10:11], s[82:83], v[32:33] op_sel_hi:[1,0,0]
	v_pk_fma_f32 v[94:95], v[8:9], s[82:83], v[32:33] op_sel_hi:[1,0,0]
	v_pk_fma_f32 v[134:135], v[6:7], s[82:83], v[32:33] op_sel_hi:[1,0,0]
	v_pk_fma_f32 v[136:137], v[4:5], s[82:83], v[32:33] op_sel_hi:[1,0,0]
	v_or3_b32 v151, v1, v2, v3
	s_cmp_ge_i32 s8, s77
	v_cmp_gt_u32_e64 s[8:9], 32, v144
	v_lshl_add_u32 v147, v148, 2, v0
	v_lshl_add_u32 v145, v157, 2, v0
	s_cbranch_scc1 .LBB0_221
	v_mov_b32_e32 v150, 0
	s_mov_b64 s[92:93], s[14:15]
	s_mov_b64 s[14:15], s[12:13]
	s_mov_b32 s12, s71
	s_mov_b32 s71, s46
	s_mov_b32 s70, s37
	s_mov_b32 s10, 2
	v_subrev_u32_e32 v128, s2, v157
	s_mov_b32 s2, 0
	s_sub_i32 s18, 0, s77
	s_add_i32 s19, s3, 3
	s_mov_b32 s86, 1
	v_mov_b32_e32 v166, v144
	v_mov_b32_e32 v16, 0
	v_mov_b32_e32 v17, v150
	v_mov_b32_e32 v18, v150
	v_mov_b32_e32 v19, v150
	v_mov_b32_e32 v20, v150
	v_mov_b32_e32 v21, v150
	v_mov_b32_e32 v22, v150
	v_mov_b32_e32 v23, v150
	v_mov_b32_e32 v24, v150
	v_mov_b32_e32 v25, v150
	v_mov_b32_e32 v26, v150
	v_mov_b32_e32 v27, v150
	v_mov_b32_e32 v28, v150
	v_mov_b32_e32 v29, v150
	v_mov_b32_e32 v30, v150
	v_mov_b32_e32 v31, v150
	v_mov_b32_e32 v0, 0
	v_mov_b32_e32 v1, v150
	v_mov_b32_e32 v2, v150
	v_mov_b32_e32 v3, v150
	v_mov_b32_e32 v4, v150
	v_mov_b32_e32 v5, v150
	v_mov_b32_e32 v6, v150
	v_mov_b32_e32 v7, v150
	v_mov_b32_e32 v8, v150
	v_mov_b32_e32 v9, v150
	v_mov_b32_e32 v10, v150
	v_mov_b32_e32 v11, v150
	v_mov_b32_e32 v12, v150
	v_mov_b32_e32 v13, v150
	v_mov_b32_e32 v14, v150
	v_mov_b32_e32 v15, v150
	v_add_u32_e32 v248, s78, v158
	v_add_u32_e32 v248, 0xc0, v248
	v_lshlrev_b32_e32 v248, 11, v248
	v_lshl_or_b32 v248, v159, 1, v248
	v_add_u32_e32 v249, s78, v166
	v_add_u32_e32 v249, 0xc0, v249
	v_lshlrev_b32_e32 v249, 2, v249
	.p2align 6

.LBB0_1539:
	s_or_b64 exec, exec, s[24:25]
	s_waitcnt vmcnt(63)
	s_mov_b32 s18, -2
	s_mov_b64 s[24:25], s[22:23]
	s_mov_b64 s[42:43], s[14:15]
	s_barrier
	s_barrier
	.p2align 6

.LBB0_1559:
	s_or_b64 exec, exec, s[22:23]
	s_waitcnt vmcnt(63)
	s_mov_b32 s38, -2
	s_mov_b64 s[22:23], s[18:19]
	s_mov_b64 s[24:25], s[14:15]
	s_barrier
	s_barrier
	.p2align 6
